# q6 layer-1 weight conversion by a hand-written transposer with the next tile's loads in flight
# baseline (speedup 1.0000x reference)
.LBB0_1194:
	s_cmpk_eq_i32 s72, 0x100
	v_readlane_b32 s4, v239, 40
	s_cselect_b64 s[2:3], -1, 0
	v_readlane_b32 s5, v239, 41
	s_and_b64 s[2:3], s[4:5], s[2:3]
	s_cmp_gt_i32 s58, 11
	s_cselect_b64 s[4:5], -1, 0
	s_and_b64 s[2:3], s[2:3], s[4:5]
	s_add_i32 s8, s58, -12
	s_cmpk_lt_u32 s8, 0x18e0
	s_cselect_b64 s[4:5], -1, 0
	s_and_b64 s[2:3], s[2:3], s[4:5]
	v_readlane_b32 s72, v241, 47
	s_andn2_b64 vcc, exec, s[2:3]
	v_readlane_b32 s73, v241, 48
	s_cbranch_vccnz .LBB0_1217
	s_mov_b32 s56, s8
	s_mov_b32 s8, 1
	v_readlane_b32 s14, v239, 42
	v_readlane_b32 s15, v239, 43
	v_lshrrev_b32_e32 v117, 5, v178
	v_and_b32_e32 v168, 31, v178
	v_lshlrev_b32_e32 v116, 2, v168
	v_mul_u32_u24_e32 v16, 0x204, v117
	v_lshl_add_u32 v16, v116, 2, v16
	v_and_b32_e32 v168, 7, v178
	v_lshlrev_b32_e32 v120, 4, v168
	v_mul_u32_u24_e32 v17, 0x1020, v168
	v_lshrrev_b32_e32 v119, 3, v178
	v_lshl_add_u32 v17, v119, 2, v17
	s_add_i32 s4, s56, 0
	s_mov_b32 s39, 0
	s_cmpk_lt_u32 s4, 0x6c0
	s_cbranch_scc0 .Ltrq6_t1_0
	s_lshr_b32 s5, s4, 5
	s_and_b32 s6, s4, 31
	v_readlane_b32 s28, v241, 11
	v_readlane_b32 s29, v241, 12
	s_mul_i32 s30, s8, 0x3430000
	s_movk_i32 s38, 0x6860
	s_mov_b32 s2, 0
	s_mul_i32 s3, s8, 0x1b00000
	s_movk_i32 s44, 0x1000
	s_mov_b32 s39, 1
	s_branch .Ltrq6_dec_0
.Ltrq6_t1_0:
	s_sub_i32 s4, s4, 0x6c0
	s_cmpk_lt_u32 s4, 0x200
	s_cbranch_scc0 .Ltrq6_t2_0
	s_lshr_b32 s5, s4, 5
	s_and_b32 s6, s4, 31
	v_readlane_b32 s28, v241, 31
	v_readlane_b32 s29, v241, 32
	s_lshl_b32 s30, s8, 24
	s_movk_i32 s38, 0x2000
	s_mov_b32 s2, 0x3600000
	s_lshl_b32 s3, s8, 23
	s_movk_i32 s44, 0x1000
	s_branch .Ltrq6_dec_0
.Ltrq6_t2_0:
	s_sub_i32 s4, s4, 0x200
	s_cmpk_lt_u32 s4, 0xac0
	s_cbranch_scc0 .Ltrq6_t3_0
	s_lshr_b32 s5, s4, 5
	s_and_b32 s6, s4, 31
	v_readlane_b32 s28, v241, 37
	v_readlane_b32 s29, v241, 38
	s_mul_i32 s30, s8, 0x5600000
	s_mov_b32 s38, 0xac00
	s_mov_b32 s2, 0x4600000
	s_mul_i32 s3, s8, 0x2b00000
	s_movk_i32 s44, 0x1000
	s_branch .Ltrq6_dec_0
.Ltrq6_t3_0:
	s_sub_i32 s4, s4, 0xac0
	s_mul_hi_u32 s5, s4, 0x2fa0be9
	s_mul_i32 s6, s5, 86
	s_sub_i32 s6, s4, s6
	v_readlane_b32 s28, v241, 1
	v_readlane_b32 s29, v241, 2
	s_mul_i32 s30, s8, 0x2b00000
	s_movk_i32 s38, 0x2000
	s_mov_b32 s2, 0x9c00000
	s_mul_i32 s3, s8, 0x1580000
	s_movk_i32 s44, 0x2b00
.Ltrq6_dec_0:
	s_add_u32 s28, s28, s30
	s_addc_u32 s29, s29, 0
	s_lshl_b32 s40, s5, 7
	s_lshl_b32 s30, s6, 6
	s_mul_i32 s30, s30, s38
	s_add_u32 s36, s28, s30
	s_addc_u32 s37, s29, 0
	s_add_u32 s42, s14, s2
	s_addc_u32 s43, s15, 0
	s_add_u32 s42, s42, s3
	s_addc_u32 s43, s43, 0
	s_mul_i32 s30, s40, s44
	s_lshl_b32 s2, s6, 7
	s_add_u32 s30, s30, s2
	s_add_u32 s42, s42, s30
	s_addc_u32 s43, s43, 0
	s_lshr_b32 s30, s40, 10
	s_cmp_eq_u32 s30, 1
	s_cselect_b32 s45, s39, 0
	v_add_u32_e32 v19, s40, v116
	s_mov_b64 s[12:13], 0
	s_cmp_eq_u32 s39, 0
	s_cbranch_scc1 .Ltrq6_m0_1
	v_add_u32_e32 v168, 8, v19
	v_cmp_gt_u32_e32 vcc, 0x1000, v19
	s_nop 1
	v_cndmask_b32_e32 v168, v168, v19, vcc
	v_add_u32_e32 v118, 0xfffff600, v19
	v_cmp_gt_u32_e32 vcc, 0x1a00, v19
	s_nop 1
	v_cndmask_b32_e32 v168, v118, v168, vcc
	v_cmp_gt_u32_e32 vcc, 0x1a08, v19
	s_nop 1
	v_cndmask_b32_e32 v168, v19, v168, vcc
	s_movk_i32 s30, 0x1a18
	v_cmp_le_u32_e64 s[12:13], s30, v19
	s_nop 1
	v_cndmask_b32_e64 v19, v168, 0, s[12:13]
.Ltrq6_m0_1:
	v_lshlrev_b32_e32 v19, 2, v19
	v_mad_u32_u24 v18, v117, s38, v19
	s_lshl_b32 s30, s38, 4
	global_load_dwordx4 v[100:103], v18, s[36:37] nt
	s_add_u32 s36, s36, s30
	s_addc_u32 s37, s37, 0
	global_load_dwordx4 v[104:107], v18, s[36:37] nt
	s_add_u32 s36, s36, s30
	s_addc_u32 s37, s37, 0
	global_load_dwordx4 v[108:111], v18, s[36:37] nt
	s_add_u32 s36, s36, s30
	s_addc_u32 s37, s37, 0
	global_load_dwordx4 v[112:115], v18, s[36:37] nt
	s_waitcnt vmcnt(0)
.Ltrq6_top:
	s_mov_b64 s[46:47], s[42:43]
	s_mov_b32 s48, s44
	s_mov_b32 s49, s45
	s_mov_b64 s[50:51], s[12:13]
	v_mad_u32_u24 v20, v119, s48, v120
	s_lshl_b32 s30, s48, 6
	v_add_u32_e32 v21, s30, v20
	s_waitcnt vmcnt(2)
	v_cndmask_b32_e64 v100, v100, 0, s[50:51]
	v_cndmask_b32_e64 v101, v101, 0, s[50:51]
	v_cndmask_b32_e64 v102, v102, 0, s[50:51]
	v_cndmask_b32_e64 v103, v103, 0, s[50:51]
	v_cndmask_b32_e64 v104, v104, 0, s[50:51]
	v_cndmask_b32_e64 v105, v105, 0, s[50:51]
	v_cndmask_b32_e64 v106, v106, 0, s[50:51]
	v_cndmask_b32_e64 v107, v107, 0, s[50:51]
	v_cndmask_b32_e64 v108, v108, 0, s[50:51]
	v_cndmask_b32_e64 v109, v109, 0, s[50:51]
	v_cndmask_b32_e64 v110, v110, 0, s[50:51]
	v_cndmask_b32_e64 v111, v111, 0, s[50:51]
	v_cndmask_b32_e64 v112, v112, 0, s[50:51]
	v_cndmask_b32_e64 v113, v113, 0, s[50:51]
	v_cndmask_b32_e64 v114, v114, 0, s[50:51]
	v_cndmask_b32_e64 v115, v115, 0, s[50:51]
	s_cmp_eq_u32 s49, 0
	s_cbranch_scc1 .Ltrq6_nosc
	v_mul_f32_e32 v100, 0x3d800000, v100
	v_mul_f32_e32 v101, 0x3d800000, v101
	v_mul_f32_e32 v102, 0x3d800000, v102
	v_mul_f32_e32 v103, 0x3d800000, v103
	v_mul_f32_e32 v104, 0x3d800000, v104
	v_mul_f32_e32 v105, 0x3d800000, v105
	v_mul_f32_e32 v106, 0x3d800000, v106
	v_mul_f32_e32 v107, 0x3d800000, v107
	v_mul_f32_e32 v108, 0x3d800000, v108
	v_mul_f32_e32 v109, 0x3d800000, v109
	v_mul_f32_e32 v110, 0x3d800000, v110
	v_mul_f32_e32 v111, 0x3d800000, v111
	v_mul_f32_e32 v112, 0x3d800000, v112
	v_mul_f32_e32 v113, 0x3d800000, v113
	v_mul_f32_e32 v114, 0x3d800000, v114
	v_mul_f32_e32 v115, 0x3d800000, v115
.Ltrq6_nosc:
	v_mov_b32_e32 v168, v16
	ds_write2_b32 v168, v100, v101 offset1:1
	ds_write2_b32 v168, v102, v103 offset0:2 offset1:3
	v_add_u32_e32 v168, 8256, v16
	ds_write2_b32 v168, v104, v105 offset1:1
	ds_write2_b32 v168, v106, v107 offset0:2 offset1:3
	v_add_u32_e32 v168, 16512, v16
	ds_write2_b32 v168, v108, v109 offset1:1
	ds_write2_b32 v168, v110, v111 offset0:2 offset1:3
	v_add_u32_e32 v168, 24768, v16
	ds_write2_b32 v168, v112, v113 offset1:1
	ds_write2_b32 v168, v114, v115 offset0:2 offset1:3
	s_add_i32 s56, s56, 244
	s_cmpk_lt_u32 s56, 0x18e0
	s_cselect_b32 s7, 1, 0
	s_cbranch_scc0 .Ltrq6_nonext
	s_add_i32 s4, s56, 0
	s_mov_b32 s39, 0
	s_cmpk_lt_u32 s4, 0x6c0
	s_cbranch_scc0 .Ltrq6_t1_1
	s_lshr_b32 s5, s4, 5
	s_and_b32 s6, s4, 31
	v_readlane_b32 s28, v241, 11
	v_readlane_b32 s29, v241, 12
	s_mul_i32 s30, s8, 0x3430000
	s_movk_i32 s38, 0x6860
	s_mov_b32 s2, 0
	s_mul_i32 s3, s8, 0x1b00000
	s_movk_i32 s44, 0x1000
	s_mov_b32 s39, 1
	s_branch .Ltrq6_dec_1

.Ltrq6_m0_2:
	v_lshlrev_b32_e32 v19, 2, v19
	v_mad_u32_u24 v18, v117, s38, v19
	s_lshl_b32 s30, s38, 4
	global_load_dwordx4 v[100:103], v18, s[36:37] nt
	s_add_u32 s36, s36, s30
	s_addc_u32 s37, s37, 0
	global_load_dwordx4 v[104:107], v18, s[36:37] nt
	s_add_u32 s36, s36, s30
	s_addc_u32 s37, s37, 0
	global_load_dwordx4 v[108:111], v18, s[36:37] nt
	s_add_u32 s36, s36, s30
	s_addc_u32 s37, s37, 0
	global_load_dwordx4 v[112:115], v18, s[36:37] nt
.Ltrq6_nonext:
	s_waitcnt lgkmcnt(0)
	s_barrier
	ds_read_b32 v0, v17
	ds_read_b32 v1, v17 offset:516
	ds_read_b32 v2, v17 offset:1032
	ds_read_b32 v3, v17 offset:1548
	ds_read_b32 v4, v17 offset:2064
	ds_read_b32 v5, v17 offset:2580
	ds_read_b32 v6, v17 offset:3096
	ds_read_b32 v7, v17 offset:3612
	ds_read_b32 v8, v17 offset:256
	ds_read_b32 v9, v17 offset:772
	ds_read_b32 v10, v17 offset:1288
	ds_read_b32 v11, v17 offset:1804
	ds_read_b32 v12, v17 offset:2320
	ds_read_b32 v13, v17 offset:2836
	ds_read_b32 v14, v17 offset:3352
	ds_read_b32 v15, v17 offset:3868
	s_waitcnt lgkmcnt(8)
	v_cvt_pk_bf16_f32 v0, v0, v1
	v_cvt_pk_bf16_f32 v1, v2, v3
	v_cvt_pk_bf16_f32 v2, v4, v5
	v_cvt_pk_bf16_f32 v3, v6, v7
	global_store_dwordx4 v20, v[0:3], s[46:47]
	s_waitcnt lgkmcnt(0)
	v_cvt_pk_bf16_f32 v8, v8, v9
	v_cvt_pk_bf16_f32 v9, v10, v11
	v_cvt_pk_bf16_f32 v10, v12, v13
	v_cvt_pk_bf16_f32 v11, v14, v15
	global_store_dwordx4 v21, v[8:11], s[46:47]
	s_barrier
	s_cmp_lg_u32 s7, 0
	s_cbranch_scc1 .Ltrq6_top
	s_branch .LBB0_1217
